# ph4 gates epilogue: (x+b)*-log2e folded to one fma with pre-scaled bias, (la+la)*log2e to one mul
# baseline (speedup 1.0000x reference)
.LBB0_1002:
	v_mov_b32_e32 v243, 0xbfb8aa3b
	v_mov_b32_e32 v66, v179
	s_and_b32 s2, s1, 1
	v_ashrrev_i32_e32 v67, 2, v66
	v_and_b32_e32 v67, 0xffffffc0, v67
	v_lshl_add_u32 v67, s0, 8, v67
	v_and_or_b32 v222, v66, 15, v67
	s_lshl_b32 s0, s1, 6
	v_lshrrev_b32_e32 v66, 1, v66
	s_and_b32 s0, s0, 0xffffff80
	v_and_b32_e32 v66, 0x78, v66
	v_or_b32_e32 v162, s0, v66
	s_mul_i32 s0, s2, 0x5000000
	v_ashrrev_i32_e32 v163, 31, v162
	s_add_u32 s0, s73, s0
	s_addc_u32 s1, s21, 0
	v_lshlrev_b64 v[170:171], 2, v[162:163]
	s_lshl_b32 s2, s2, 12
	v_lshl_add_u64 v[204:205], s[0:1], 0, v[170:171]
	s_add_u32 s0, s34, s2
	s_addc_u32 s1, s35, 0
	v_lshl_add_u64 v[206:207], s[0:1], 0, v[170:171]
	v_lshl_add_u64 v[66:67], v[162:163], 1, s[42:43]
	global_load_dwordx4 v[162:165], v[206:207], off
	s_add_u32 s0, s30, s2
	s_addc_u32 s1, s31, 0
	v_lshl_add_u64 v[208:209], s[0:1], 0, v[170:171]
	s_add_u32 s0, s16, s2
	v_ashrrev_i32_e32 v223, 31, v222
	s_addc_u32 s1, s17, 0
	v_lshlrev_b64 v[70:71], 11, v[222:223]
	v_lshl_add_u64 v[210:211], s[0:1], 0, v[170:171]
	v_lshl_add_u64 v[70:71], v[66:67], 0, v[70:71]
	global_load_dwordx4 v[170:173], v[210:211], off
	global_load_dwordx4 v[158:161], v[70:71], off
	global_load_dwordx4 v[166:169], v[208:209], off
	v_add_u32_e32 v214, 0x80, v222
	v_ashrrev_i32_e32 v215, 31, v214
	v_lshlrev_b64 v[68:69], 11, v[214:215]
	v_lshl_add_u64 v[68:69], v[66:67], 0, v[68:69]
	global_load_dwordx4 v[86:89], v[68:69], off
	v_or_b32_e32 v220, 16, v222
	v_add_u32_e32 v212, 0x90, v222
	v_ashrrev_i32_e32 v221, 31, v220
	v_ashrrev_i32_e32 v213, 31, v212
	v_lshlrev_b64 v[70:71], 11, v[220:221]
	v_or_b32_e32 v218, 32, v222
	v_lshlrev_b64 v[68:69], 11, v[212:213]
	v_lshl_add_u64 v[70:71], v[66:67], 0, v[70:71]
	v_ashrrev_i32_e32 v219, 31, v218
	v_lshl_add_u64 v[68:69], v[66:67], 0, v[68:69]
	global_load_dwordx4 v[122:125], v[70:71], off
	global_load_dwordx4 v[74:77], v[68:69], off
	v_lshlrev_b64 v[70:71], 11, v[218:219]
	v_or_b32_e32 v216, 48, v222
	v_add_u32_e32 v202, 0xa0, v222
	v_lshl_add_u64 v[70:71], v[66:67], 0, v[70:71]
	v_ashrrev_i32_e32 v217, 31, v216
	v_ashrrev_i32_e32 v203, 31, v202
	global_load_dwordx4 v[110:113], v[70:71], off
	v_lshlrev_b64 v[70:71], 11, v[216:217]
	v_lshlrev_b64 v[68:69], 11, v[202:203]
	v_add_u32_e32 v200, 0xb0, v222
	v_lshl_add_u64 v[70:71], v[66:67], 0, v[70:71]
	v_lshl_add_u64 v[68:69], v[66:67], 0, v[68:69]
	v_ashrrev_i32_e32 v201, 31, v200
	global_load_dwordx4 v[98:101], v[70:71], off
	s_waitcnt vmcnt(0)
	v_mul_f32_e32 v162, 0xbfb8aa3b, v162
	v_mul_f32_e32 v163, 0xbfb8aa3b, v163
	v_mul_f32_e32 v164, 0xbfb8aa3b, v164
	v_mul_f32_e32 v165, 0xbfb8aa3b, v165
	v_mul_f32_e32 v166, 0xbfb8aa3b, v166
	v_mul_f32_e32 v167, 0xbfb8aa3b, v167
	v_mul_f32_e32 v168, 0xbfb8aa3b, v168
	v_mul_f32_e32 v169, 0xbfb8aa3b, v169
	v_fma_f32 v154, v154, v243, v162
	v_exp_f32_e32 v154, v154
	global_load_dwordx4 v[70:73], v[68:69], off
	v_lshlrev_b64 v[68:69], 11, v[200:201]
	v_lshl_add_u64 v[66:67], v[66:67], 0, v[68:69]
	v_add_f32_e32 v154, 1.0, v154
	v_rcp_f32_e64 v154, -v154
	global_load_dwordx4 v[66:69], v[66:67], off
	v_mul_f32_e32 v154, v170, v154
	v_lshlrev_b32_e32 v227, 16, v158
	v_and_b32_e32 v228, 0xffff0000, v158
	v_lshlrev_b32_e32 v226, 16, v159
	v_and_b32_e32 v158, 0xffff0000, v159
	v_mul_f32_e32 v159, 0x4038aa3b, v154
	v_exp_f32_e32 v159, v159
	v_fma_f32 v150, v150, v243, v166
	v_exp_f32_e32 v150, v150
	v_sub_f32_e32 v159, 1.0, v159
	v_max_f32_e32 v159, 0x1e3ce508, v159
	v_add_f32_e32 v150, 1.0, v150
	v_mul_f32_e32 v229, v150, v159
	v_mul_f32_e32 v150, v150, v229
	v_rsq_f32_e32 v150, v150
	v_fma_f32 v151, v151, v243, v167
	v_exp_f32_e32 v151, v151
	v_mul_f32_e32 v150, v159, v150
	v_mul_f32_e32 v150, v150, v227
	v_cvt_pk_bf16_f32 v150, v154, v150
	v_fma_f32 v154, v155, v243, v163
	v_exp_f32_e32 v154, v154
	v_add_f32_e32 v151, 1.0, v151
	v_fma_f32 v152, v152, v243, v168
	v_exp_f32_e32 v152, v152
	v_add_f32_e32 v154, 1.0, v154
	v_rcp_f32_e64 v154, -v154
	v_add_f32_e32 v152, 1.0, v152
	v_fma_f32 v153, v153, v243, v169
	v_mul_f32_e32 v154, v171, v154
	v_mul_f32_e32 v155, 0x4038aa3b, v154
	v_exp_f32_e32 v155, v155
	v_exp_f32_e32 v153, v153
	v_sub_f32_e32 v155, 1.0, v155
	v_max_f32_e32 v155, 0x1e3ce508, v155
	v_mul_f32_e32 v159, v151, v155
	v_mul_f32_e32 v151, v151, v159
	v_rsq_f32_e32 v151, v151
	v_add_f32_e32 v153, 1.0, v153
	v_mul_f32_e32 v151, v155, v151
	v_mul_f32_e32 v151, v151, v228
	v_cvt_pk_bf16_f32 v151, v154, v151
	v_fma_f32 v154, v156, v243, v164
	v_exp_f32_e32 v154, v154
	s_nop 0
	v_add_f32_e32 v154, 1.0, v154
	v_rcp_f32_e64 v154, -v154
	s_nop 0
	v_mul_f32_e32 v154, v172, v154
	v_mul_f32_e32 v155, 0x4038aa3b, v154
	v_exp_f32_e32 v155, v155
	s_nop 0
	v_sub_f32_e32 v155, 1.0, v155
	v_max_f32_e32 v155, 0x1e3ce508, v155
	v_mul_f32_e32 v156, v152, v155
	v_mul_f32_e32 v152, v152, v156
	v_rsq_f32_e32 v152, v152
	s_nop 0
	v_mul_f32_e32 v152, v155, v152
	v_mul_f32_e32 v152, v152, v226
	v_cvt_pk_bf16_f32 v152, v154, v152
	v_fma_f32 v154, v157, v243, v165
	v_exp_f32_e32 v154, v154
	s_nop 0
	v_add_f32_e32 v154, 1.0, v154
	v_rcp_f32_e64 v154, -v154
	s_nop 0
	v_mul_f32_e32 v154, v173, v154
	v_mul_f32_e32 v155, 0x4038aa3b, v154
	v_exp_f32_e32 v155, v155
	s_nop 0
	v_sub_f32_e32 v155, 1.0, v155
	v_max_f32_e32 v155, 0x1e3ce508, v155
	v_mul_f32_e32 v156, v153, v155
	v_mul_f32_e32 v153, v153, v156
	v_rsq_f32_e32 v153, v153
	s_nop 0
	v_mul_f32_e32 v153, v155, v153
	v_mul_f32_e32 v153, v153, v158
	v_cvt_pk_bf16_f32 v153, v154, v153
	v_lshlrev_b64 v[154:155], 12, v[222:223]
	v_lshl_add_u64 v[154:155], v[204:205], 0, v[154:155]
	global_store_dwordx4 v[154:155], v[150:153], off
	v_fma_f32 v146, v146, v243, v162
	v_exp_f32_e32 v146, v146
	v_fma_f32 v142, v142, v243, v166
	v_exp_f32_e32 v142, v142
	v_add_f32_e32 v146, 1.0, v146
	v_rcp_f32_e64 v146, -v146
	v_fma_f32 v147, v147, v243, v163
	v_add_f32_e32 v142, 1.0, v142
	v_mul_f32_e32 v146, v170, v146
	v_mul_f32_e32 v152, 0x4038aa3b, v146
	v_exp_f32_e32 v152, v152
	v_exp_f32_e32 v147, v147
	v_lshlrev_b32_e32 v150, 16, v122
	v_sub_f32_e32 v152, 1.0, v152
	v_max_f32_e32 v152, 0x1e3ce508, v152
	v_mul_f32_e32 v153, v142, v152
	v_mul_f32_e32 v142, v142, v153
	v_rsq_f32_e32 v142, v142
	v_add_f32_e32 v147, 1.0, v147
	v_rcp_f32_e64 v147, -v147
	v_fma_f32 v143, v143, v243, v167
	v_mul_f32_e32 v142, v152, v142
	v_mul_f32_e32 v142, v142, v150
	v_cvt_pk_bf16_f32 v142, v146, v142
	v_mul_f32_e32 v146, v171, v147
	v_mul_f32_e32 v147, 0x4038aa3b, v146
	v_exp_f32_e32 v147, v147
	v_exp_f32_e32 v143, v143
	v_fma_f32 v148, v148, v243, v164
	v_sub_f32_e32 v147, 1.0, v147
	v_max_f32_e32 v147, 0x1e3ce508, v147
	v_add_f32_e32 v143, 1.0, v143
	v_exp_f32_e32 v148, v148
	v_mul_f32_e32 v150, v143, v147
	v_mul_f32_e32 v143, v143, v150
	v_rsq_f32_e32 v143, v143
	v_add_f32_e32 v148, 1.0, v148
	v_rcp_f32_e64 v148, -v148
	v_and_b32_e32 v122, 0xffff0000, v122
	v_mul_f32_e32 v143, v147, v143
	v_mul_f32_e32 v122, v143, v122
	v_cvt_pk_bf16_f32 v143, v146, v122
	v_fma_f32 v146, v149, v243, v165
	v_mul_f32_e32 v148, v172, v148
	v_exp_f32_e32 v146, v146
	v_mul_f32_e32 v150, 0x4038aa3b, v148
	v_exp_f32_e32 v150, v150
	v_fma_f32 v144, v144, v243, v168
	v_exp_f32_e32 v144, v144
	v_add_f32_e32 v146, 1.0, v146
	v_rcp_f32_e64 v146, -v146
	v_sub_f32_e32 v122, 1.0, v150
	v_max_f32_e32 v122, 0x1e3ce508, v122
	v_add_f32_e32 v144, 1.0, v144
	v_mul_f32_e32 v147, v144, v122
	v_mul_f32_e32 v146, v173, v146
	v_mul_f32_e32 v144, v144, v147
	v_mul_f32_e32 v147, 0x4038aa3b, v146
	v_exp_f32_e32 v147, v147
	v_fma_f32 v145, v145, v243, v169
	v_exp_f32_e32 v145, v145
	v_rsq_f32_e32 v144, v144
	v_sub_f32_e32 v147, 1.0, v147
	v_max_f32_e32 v147, 0x1e3ce508, v147
	v_add_f32_e32 v145, 1.0, v145
	v_mul_f32_e32 v149, v145, v147
	v_mul_f32_e32 v145, v145, v149
	v_rsq_f32_e32 v145, v145
	v_lshlrev_b32_e32 v151, 16, v123
	v_mul_f32_e32 v122, v122, v144
	v_mul_f32_e32 v122, v122, v151
	v_and_b32_e32 v123, 0xffff0000, v123
	v_cvt_pk_bf16_f32 v144, v148, v122
	v_mul_f32_e32 v122, v147, v145
	v_mul_f32_e32 v122, v122, v123
	v_cvt_pk_bf16_f32 v145, v146, v122
	v_lshlrev_b64 v[122:123], 12, v[220:221]
	v_lshl_add_u64 v[122:123], v[204:205], 0, v[122:123]
	global_store_dwordx4 v[122:123], v[142:145], off
	global_load_dwordx4 v[146:149], v[206:207], off offset:16
	global_load_dwordx4 v[150:153], v[208:209], off offset:16
	global_load_dwordx4 v[156:159], v[210:211], off offset:16
	v_fma_f32 v138, v138, v243, v162
	v_exp_f32_e32 v138, v138
	v_fma_f32 v134, v134, v243, v166
	v_exp_f32_e32 v134, v134
	v_add_f32_e32 v138, 1.0, v138
	v_rcp_f32_e64 v138, -v138
	v_fma_f32 v139, v139, v243, v163
	v_add_f32_e32 v134, 1.0, v134
	v_mul_f32_e32 v138, v170, v138
	v_mul_f32_e32 v144, 0x4038aa3b, v138
	v_exp_f32_e32 v144, v144
	v_exp_f32_e32 v139, v139
	v_lshlrev_b32_e32 v142, 16, v110
	v_sub_f32_e32 v144, 1.0, v144
	v_max_f32_e32 v144, 0x1e3ce508, v144
	v_mul_f32_e32 v145, v134, v144
	v_mul_f32_e32 v134, v134, v145
	v_rsq_f32_e32 v134, v134
	v_add_f32_e32 v139, 1.0, v139
	v_rcp_f32_e64 v139, -v139
	v_fma_f32 v135, v135, v243, v167
	v_mul_f32_e32 v134, v144, v134
	v_mul_f32_e32 v134, v134, v142
	v_cvt_pk_bf16_f32 v134, v138, v134
	v_mul_f32_e32 v138, v171, v139
	v_mul_f32_e32 v139, 0x4038aa3b, v138
	v_exp_f32_e32 v139, v139
	v_exp_f32_e32 v135, v135
	v_fma_f32 v140, v140, v243, v164
	v_sub_f32_e32 v139, 1.0, v139
	v_max_f32_e32 v139, 0x1e3ce508, v139
	v_add_f32_e32 v135, 1.0, v135
	v_exp_f32_e32 v140, v140
	v_mul_f32_e32 v142, v135, v139
	v_mul_f32_e32 v135, v135, v142
	v_rsq_f32_e32 v135, v135
	v_add_f32_e32 v140, 1.0, v140
	v_rcp_f32_e64 v140, -v140
	v_and_b32_e32 v110, 0xffff0000, v110
	v_mul_f32_e32 v135, v139, v135
	v_mul_f32_e32 v110, v135, v110
	v_cvt_pk_bf16_f32 v135, v138, v110
	v_fma_f32 v138, v141, v243, v165
	v_mul_f32_e32 v140, v172, v140
	v_exp_f32_e32 v138, v138
	v_mul_f32_e32 v142, 0x4038aa3b, v140
	v_exp_f32_e32 v142, v142
	v_fma_f32 v136, v136, v243, v168
	v_exp_f32_e32 v136, v136
	v_add_f32_e32 v138, 1.0, v138
	v_rcp_f32_e64 v138, -v138
	v_sub_f32_e32 v110, 1.0, v142
	v_max_f32_e32 v110, 0x1e3ce508, v110
	v_add_f32_e32 v136, 1.0, v136
	v_mul_f32_e32 v139, v136, v110
	v_mul_f32_e32 v138, v173, v138
	v_mul_f32_e32 v136, v136, v139
	v_mul_f32_e32 v139, 0x4038aa3b, v138
	v_exp_f32_e32 v139, v139
	v_fma_f32 v137, v137, v243, v169
	v_exp_f32_e32 v137, v137
	v_rsq_f32_e32 v136, v136
	v_sub_f32_e32 v139, 1.0, v139
	v_max_f32_e32 v139, 0x1e3ce508, v139
	v_add_f32_e32 v137, 1.0, v137
	v_mul_f32_e32 v141, v137, v139
	v_mul_f32_e32 v137, v137, v141
	v_rsq_f32_e32 v137, v137
	v_lshlrev_b32_e32 v143, 16, v111
	v_mul_f32_e32 v110, v110, v136
	v_mul_f32_e32 v110, v110, v143
	v_and_b32_e32 v111, 0xffff0000, v111
	v_cvt_pk_bf16_f32 v136, v140, v110
	v_mul_f32_e32 v110, v139, v137
	v_mul_f32_e32 v110, v110, v111
	v_cvt_pk_bf16_f32 v137, v138, v110
	v_lshlrev_b64 v[110:111], 12, v[218:219]
	v_lshl_add_u64 v[110:111], v[204:205], 0, v[110:111]
	global_store_dwordx4 v[110:111], v[134:137], off
	v_fma_f32 v130, v130, v243, v162
	v_exp_f32_e32 v130, v130
	v_fma_f32 v126, v126, v243, v166
	v_exp_f32_e32 v126, v126
	v_add_f32_e32 v130, 1.0, v130
	v_rcp_f32_e64 v130, -v130
	v_fma_f32 v131, v131, v243, v163
	v_add_f32_e32 v126, 1.0, v126
	v_mul_f32_e32 v130, v170, v130
	v_mul_f32_e32 v136, 0x4038aa3b, v130
	v_exp_f32_e32 v136, v136
	v_exp_f32_e32 v131, v131
	v_lshlrev_b32_e32 v134, 16, v98
	v_sub_f32_e32 v136, 1.0, v136
	v_max_f32_e32 v136, 0x1e3ce508, v136
	v_mul_f32_e32 v137, v126, v136
	v_mul_f32_e32 v126, v126, v137
	v_rsq_f32_e32 v126, v126
	v_add_f32_e32 v131, 1.0, v131
	v_rcp_f32_e64 v131, -v131
	v_fma_f32 v127, v127, v243, v167
	v_mul_f32_e32 v126, v136, v126
	v_mul_f32_e32 v126, v126, v134
	v_cvt_pk_bf16_f32 v126, v130, v126
	v_mul_f32_e32 v130, v171, v131
	v_mul_f32_e32 v131, 0x4038aa3b, v130
	v_exp_f32_e32 v131, v131
	v_exp_f32_e32 v127, v127
	v_fma_f32 v132, v132, v243, v164
	v_sub_f32_e32 v131, 1.0, v131
	v_max_f32_e32 v131, 0x1e3ce508, v131
	v_add_f32_e32 v127, 1.0, v127
	v_exp_f32_e32 v132, v132
	v_mul_f32_e32 v134, v127, v131
	v_mul_f32_e32 v127, v127, v134
	v_rsq_f32_e32 v127, v127
	v_add_f32_e32 v132, 1.0, v132
	v_rcp_f32_e64 v132, -v132
	v_and_b32_e32 v98, 0xffff0000, v98
	v_mul_f32_e32 v127, v131, v127
	v_mul_f32_e32 v98, v127, v98
	v_cvt_pk_bf16_f32 v127, v130, v98
	v_fma_f32 v130, v133, v243, v165
	v_mul_f32_e32 v132, v172, v132
	v_exp_f32_e32 v130, v130
	v_mul_f32_e32 v134, 0x4038aa3b, v132
	v_exp_f32_e32 v134, v134
	v_fma_f32 v128, v128, v243, v168
	v_exp_f32_e32 v128, v128
	v_add_f32_e32 v130, 1.0, v130
	v_rcp_f32_e64 v130, -v130
	v_sub_f32_e32 v98, 1.0, v134
	v_max_f32_e32 v98, 0x1e3ce508, v98
	v_add_f32_e32 v128, 1.0, v128
	v_mul_f32_e32 v131, v128, v98
	v_mul_f32_e32 v130, v173, v130
	v_mul_f32_e32 v128, v128, v131
	v_mul_f32_e32 v131, 0x4038aa3b, v130
	v_exp_f32_e32 v131, v131
	v_fma_f32 v129, v129, v243, v169
	v_exp_f32_e32 v129, v129
	v_rsq_f32_e32 v128, v128
	v_sub_f32_e32 v131, 1.0, v131
	v_max_f32_e32 v131, 0x1e3ce508, v131
	v_add_f32_e32 v129, 1.0, v129
	v_mul_f32_e32 v133, v129, v131
	v_mul_f32_e32 v129, v129, v133
	v_rsq_f32_e32 v129, v129
	v_lshlrev_b32_e32 v135, 16, v99
	v_mul_f32_e32 v98, v98, v128
	v_mul_f32_e32 v98, v98, v135
	v_and_b32_e32 v99, 0xffff0000, v99
	v_cvt_pk_bf16_f32 v128, v132, v98
	v_mul_f32_e32 v98, v131, v129
	v_mul_f32_e32 v98, v98, v99
	v_cvt_pk_bf16_f32 v129, v130, v98
	v_lshlrev_b64 v[98:99], 12, v[216:217]
	v_lshl_add_u64 v[98:99], v[204:205], 0, v[98:99]
	global_store_dwordx4 v[98:99], v[126:129], off
	v_fma_f32 v118, v118, v243, v162
	v_exp_f32_e32 v118, v118
	v_fma_f32 v114, v114, v243, v166
	v_exp_f32_e32 v114, v114
	v_add_f32_e32 v118, 1.0, v118
	v_rcp_f32_e64 v118, -v118
	v_fma_f32 v119, v119, v243, v163
	v_add_f32_e32 v114, 1.0, v114
	v_mul_f32_e32 v118, v170, v118
	v_mul_f32_e32 v128, 0x4038aa3b, v118
	v_exp_f32_e32 v128, v128
	v_exp_f32_e32 v119, v119
	v_lshlrev_b32_e32 v126, 16, v86
	v_sub_f32_e32 v128, 1.0, v128
	v_max_f32_e32 v128, 0x1e3ce508, v128
	v_mul_f32_e32 v129, v114, v128
	v_mul_f32_e32 v114, v114, v129
	v_rsq_f32_e32 v114, v114
	v_add_f32_e32 v119, 1.0, v119
	v_rcp_f32_e64 v119, -v119
	v_fma_f32 v115, v115, v243, v167
	v_mul_f32_e32 v114, v128, v114
	v_mul_f32_e32 v114, v114, v126
	v_cvt_pk_bf16_f32 v114, v118, v114
	v_mul_f32_e32 v118, v171, v119
	v_mul_f32_e32 v119, 0x4038aa3b, v118
	v_exp_f32_e32 v119, v119
	v_exp_f32_e32 v115, v115
	v_fma_f32 v120, v120, v243, v164
	v_sub_f32_e32 v119, 1.0, v119
	v_max_f32_e32 v119, 0x1e3ce508, v119
	v_add_f32_e32 v115, 1.0, v115
	v_exp_f32_e32 v120, v120
	v_mul_f32_e32 v126, v115, v119
	v_mul_f32_e32 v115, v115, v126
	v_rsq_f32_e32 v115, v115
	v_add_f32_e32 v120, 1.0, v120
	v_rcp_f32_e64 v120, -v120
	v_and_b32_e32 v86, 0xffff0000, v86
	v_mul_f32_e32 v115, v119, v115
	v_mul_f32_e32 v86, v115, v86
	v_cvt_pk_bf16_f32 v115, v118, v86
	v_fma_f32 v118, v121, v243, v165
	v_mul_f32_e32 v120, v172, v120
	v_exp_f32_e32 v118, v118
	v_mul_f32_e32 v126, 0x4038aa3b, v120
	v_exp_f32_e32 v126, v126
	v_fma_f32 v116, v116, v243, v168
	v_exp_f32_e32 v116, v116
	v_add_f32_e32 v118, 1.0, v118
	v_rcp_f32_e64 v118, -v118
	v_sub_f32_e32 v86, 1.0, v126
	v_max_f32_e32 v86, 0x1e3ce508, v86
	v_add_f32_e32 v116, 1.0, v116
	v_mul_f32_e32 v119, v116, v86
	v_mul_f32_e32 v118, v173, v118
	v_mul_f32_e32 v116, v116, v119
	v_mul_f32_e32 v119, 0x4038aa3b, v118
	v_exp_f32_e32 v119, v119
	v_fma_f32 v117, v117, v243, v169
	v_exp_f32_e32 v117, v117
	v_rsq_f32_e32 v116, v116
	v_sub_f32_e32 v119, 1.0, v119
	v_max_f32_e32 v119, 0x1e3ce508, v119
	v_add_f32_e32 v117, 1.0, v117
	v_mul_f32_e32 v121, v117, v119
	v_mul_f32_e32 v117, v117, v121
	v_rsq_f32_e32 v117, v117
	v_lshlrev_b32_e32 v127, 16, v87
	v_mul_f32_e32 v86, v86, v116
	v_mul_f32_e32 v86, v86, v127
	v_and_b32_e32 v87, 0xffff0000, v87
	v_cvt_pk_bf16_f32 v116, v120, v86
	v_mul_f32_e32 v86, v119, v117
	v_mul_f32_e32 v86, v86, v87
	v_cvt_pk_bf16_f32 v117, v118, v86
	v_lshlrev_b64 v[86:87], 12, v[214:215]
	v_lshl_add_u64 v[86:87], v[204:205], 0, v[86:87]
	global_store_dwordx4 v[86:87], v[114:117], off
	v_fma_f32 v106, v106, v243, v162
	v_exp_f32_e32 v106, v106
	v_fma_f32 v102, v102, v243, v166
	v_exp_f32_e32 v102, v102
	v_add_f32_e32 v106, 1.0, v106
	v_rcp_f32_e64 v106, -v106
	v_fma_f32 v107, v107, v243, v163
	v_add_f32_e32 v102, 1.0, v102
	v_mul_f32_e32 v106, v170, v106
	v_mul_f32_e32 v116, 0x4038aa3b, v106
	v_exp_f32_e32 v116, v116
	v_exp_f32_e32 v107, v107
	v_lshlrev_b32_e32 v114, 16, v74
	v_sub_f32_e32 v116, 1.0, v116
	v_max_f32_e32 v116, 0x1e3ce508, v116
	v_mul_f32_e32 v117, v102, v116
	v_mul_f32_e32 v102, v102, v117
	v_rsq_f32_e32 v102, v102
	v_add_f32_e32 v107, 1.0, v107
	v_rcp_f32_e64 v107, -v107
	v_fma_f32 v103, v103, v243, v167
	v_mul_f32_e32 v102, v116, v102
	v_mul_f32_e32 v102, v102, v114
	v_cvt_pk_bf16_f32 v102, v106, v102
	v_mul_f32_e32 v106, v171, v107
	v_mul_f32_e32 v107, 0x4038aa3b, v106
	v_exp_f32_e32 v107, v107
	v_exp_f32_e32 v103, v103
	v_fma_f32 v108, v108, v243, v164
	v_sub_f32_e32 v107, 1.0, v107
	v_max_f32_e32 v107, 0x1e3ce508, v107
	v_add_f32_e32 v103, 1.0, v103
	v_exp_f32_e32 v108, v108
	v_mul_f32_e32 v114, v103, v107
	v_mul_f32_e32 v103, v103, v114
	v_rsq_f32_e32 v103, v103
	v_add_f32_e32 v108, 1.0, v108
	v_rcp_f32_e64 v108, -v108
	v_and_b32_e32 v74, 0xffff0000, v74
	v_mul_f32_e32 v103, v107, v103
	v_mul_f32_e32 v74, v103, v74
	v_cvt_pk_bf16_f32 v103, v106, v74
	v_fma_f32 v106, v109, v243, v165
	v_mul_f32_e32 v108, v172, v108
	v_exp_f32_e32 v106, v106
	v_mul_f32_e32 v114, 0x4038aa3b, v108
	v_exp_f32_e32 v114, v114
	v_fma_f32 v104, v104, v243, v168
	v_exp_f32_e32 v104, v104
	v_add_f32_e32 v106, 1.0, v106
	v_rcp_f32_e64 v106, -v106
	v_sub_f32_e32 v74, 1.0, v114
	v_max_f32_e32 v74, 0x1e3ce508, v74
	v_add_f32_e32 v104, 1.0, v104
	v_mul_f32_e32 v107, v104, v74
	v_mul_f32_e32 v106, v173, v106
	v_mul_f32_e32 v104, v104, v107
	v_mul_f32_e32 v107, 0x4038aa3b, v106
	v_exp_f32_e32 v107, v107
	v_fma_f32 v105, v105, v243, v169
	v_exp_f32_e32 v105, v105
	v_rsq_f32_e32 v104, v104
	v_sub_f32_e32 v107, 1.0, v107
	v_max_f32_e32 v107, 0x1e3ce508, v107
	v_add_f32_e32 v105, 1.0, v105
	v_mul_f32_e32 v109, v105, v107
	v_mul_f32_e32 v105, v105, v109
	v_rsq_f32_e32 v105, v105
	v_lshlrev_b32_e32 v115, 16, v75
	v_mul_f32_e32 v74, v74, v104
	v_mul_f32_e32 v74, v74, v115
	v_and_b32_e32 v75, 0xffff0000, v75
	v_cvt_pk_bf16_f32 v104, v108, v74
	v_mul_f32_e32 v74, v107, v105
	v_mul_f32_e32 v74, v74, v75
	v_cvt_pk_bf16_f32 v105, v106, v74
	v_lshlrev_b64 v[74:75], 12, v[212:213]
	v_lshl_add_u64 v[74:75], v[204:205], 0, v[74:75]
	global_store_dwordx4 v[74:75], v[102:105], off
	v_fma_f32 v94, v94, v243, v162
	v_exp_f32_e32 v94, v94
	v_fma_f32 v90, v90, v243, v166
	v_exp_f32_e32 v90, v90
	v_add_f32_e32 v94, 1.0, v94
	v_rcp_f32_e64 v94, -v94
	v_fma_f32 v95, v95, v243, v163
	v_add_f32_e32 v90, 1.0, v90
	v_mul_f32_e32 v94, v170, v94
	v_mul_f32_e32 v104, 0x4038aa3b, v94
	v_exp_f32_e32 v104, v104
	v_exp_f32_e32 v95, v95
	s_waitcnt vmcnt(9)
	v_lshlrev_b32_e32 v102, 16, v70
	v_sub_f32_e32 v104, 1.0, v104
	v_max_f32_e32 v104, 0x1e3ce508, v104
	v_mul_f32_e32 v105, v90, v104
	v_mul_f32_e32 v90, v90, v105
	v_rsq_f32_e32 v90, v90
	v_add_f32_e32 v95, 1.0, v95
	v_rcp_f32_e64 v95, -v95
	v_fma_f32 v91, v91, v243, v167
	v_mul_f32_e32 v90, v104, v90
	v_mul_f32_e32 v90, v90, v102
	v_cvt_pk_bf16_f32 v90, v94, v90
	v_mul_f32_e32 v94, v171, v95
	v_mul_f32_e32 v95, 0x4038aa3b, v94
	v_exp_f32_e32 v95, v95
	v_exp_f32_e32 v91, v91
	v_fma_f32 v96, v96, v243, v164
	v_sub_f32_e32 v95, 1.0, v95
	v_max_f32_e32 v95, 0x1e3ce508, v95
	v_add_f32_e32 v91, 1.0, v91
	v_exp_f32_e32 v96, v96
	v_mul_f32_e32 v102, v91, v95
	v_mul_f32_e32 v91, v91, v102
	v_rsq_f32_e32 v91, v91
	v_add_f32_e32 v96, 1.0, v96
	v_rcp_f32_e64 v96, -v96
	v_and_b32_e32 v70, 0xffff0000, v70
	v_mul_f32_e32 v91, v95, v91
	v_mul_f32_e32 v70, v91, v70
	v_cvt_pk_bf16_f32 v91, v94, v70
	v_fma_f32 v94, v97, v243, v165
	v_mul_f32_e32 v96, v172, v96
	v_exp_f32_e32 v94, v94
	v_mul_f32_e32 v102, 0x4038aa3b, v96
	v_exp_f32_e32 v102, v102
	v_fma_f32 v92, v92, v243, v168
	v_exp_f32_e32 v92, v92
	v_add_f32_e32 v94, 1.0, v94
	v_rcp_f32_e64 v94, -v94
	v_sub_f32_e32 v70, 1.0, v102
	v_max_f32_e32 v70, 0x1e3ce508, v70
	v_add_f32_e32 v92, 1.0, v92
	v_mul_f32_e32 v95, v92, v70
	v_mul_f32_e32 v94, v173, v94
	v_mul_f32_e32 v92, v92, v95
	v_mul_f32_e32 v95, 0x4038aa3b, v94
	v_exp_f32_e32 v95, v95
	v_fma_f32 v93, v93, v243, v169
	v_exp_f32_e32 v93, v93
	v_rsq_f32_e32 v92, v92
	v_sub_f32_e32 v95, 1.0, v95
	v_max_f32_e32 v95, 0x1e3ce508, v95
	v_add_f32_e32 v93, 1.0, v93
	v_mul_f32_e32 v97, v93, v95
	v_mul_f32_e32 v93, v93, v97
	v_rsq_f32_e32 v93, v93
	v_lshlrev_b32_e32 v103, 16, v71
	v_mul_f32_e32 v70, v70, v92
	v_mul_f32_e32 v70, v70, v103
	v_and_b32_e32 v71, 0xffff0000, v71
	v_cvt_pk_bf16_f32 v92, v96, v70
	v_mul_f32_e32 v70, v95, v93
	v_mul_f32_e32 v70, v70, v71
	v_cvt_pk_bf16_f32 v93, v94, v70
	v_lshlrev_b64 v[70:71], 12, v[202:203]
	v_lshl_add_u64 v[70:71], v[204:205], 0, v[70:71]
	global_store_dwordx4 v[70:71], v[90:93], off
	v_fma_f32 v82, v82, v243, v162
	v_exp_f32_e32 v82, v82
	v_fma_f32 v78, v78, v243, v166
	v_exp_f32_e32 v78, v78
	v_add_f32_e32 v82, 1.0, v82
	v_rcp_f32_e64 v82, -v82
	v_fma_f32 v83, v83, v243, v163
	v_add_f32_e32 v78, 1.0, v78
	v_mul_f32_e32 v82, v170, v82
	v_mul_f32_e32 v92, 0x4038aa3b, v82
	v_exp_f32_e32 v92, v92
	v_exp_f32_e32 v83, v83
	v_lshlrev_b32_e32 v90, 16, v66
	v_sub_f32_e32 v92, 1.0, v92
	v_max_f32_e32 v92, 0x1e3ce508, v92
	v_mul_f32_e32 v93, v78, v92
	v_mul_f32_e32 v78, v78, v93
	v_rsq_f32_e32 v78, v78
	v_add_f32_e32 v83, 1.0, v83
	v_rcp_f32_e64 v83, -v83
	v_fma_f32 v79, v79, v243, v167
	v_mul_f32_e32 v78, v92, v78
	v_mul_f32_e32 v78, v78, v90
	v_cvt_pk_bf16_f32 v78, v82, v78
	v_mul_f32_e32 v82, v171, v83
	v_mul_f32_e32 v83, 0x4038aa3b, v82
	v_exp_f32_e32 v83, v83
	v_exp_f32_e32 v79, v79
	v_fma_f32 v84, v84, v243, v164
	v_sub_f32_e32 v83, 1.0, v83
	v_max_f32_e32 v83, 0x1e3ce508, v83
	v_add_f32_e32 v79, 1.0, v79
	v_exp_f32_e32 v84, v84
	v_mul_f32_e32 v90, v79, v83
	v_mul_f32_e32 v79, v79, v90
	v_rsq_f32_e32 v79, v79
	v_add_f32_e32 v84, 1.0, v84
	v_rcp_f32_e64 v84, -v84
	v_and_b32_e32 v66, 0xffff0000, v66
	v_mul_f32_e32 v79, v83, v79
	v_mul_f32_e32 v66, v79, v66
	v_cvt_pk_bf16_f32 v79, v82, v66
	v_fma_f32 v82, v85, v243, v165
	v_mul_f32_e32 v84, v172, v84
	v_exp_f32_e32 v82, v82
	v_mul_f32_e32 v90, 0x4038aa3b, v84
	v_exp_f32_e32 v90, v90
	v_fma_f32 v80, v80, v243, v168
	v_exp_f32_e32 v80, v80
	v_add_f32_e32 v82, 1.0, v82
	v_rcp_f32_e64 v82, -v82
	v_sub_f32_e32 v66, 1.0, v90
	v_max_f32_e32 v66, 0x1e3ce508, v66
	v_add_f32_e32 v80, 1.0, v80
	v_mul_f32_e32 v83, v80, v66
	v_mul_f32_e32 v82, v173, v82
	v_mul_f32_e32 v80, v80, v83
	v_mul_f32_e32 v83, 0x4038aa3b, v82
	v_exp_f32_e32 v83, v83
	v_fma_f32 v81, v81, v243, v169
	v_exp_f32_e32 v81, v81
	v_rsq_f32_e32 v80, v80
	v_sub_f32_e32 v83, 1.0, v83
	v_max_f32_e32 v83, 0x1e3ce508, v83
	v_add_f32_e32 v81, 1.0, v81
	v_mul_f32_e32 v85, v81, v83
	v_mul_f32_e32 v81, v81, v85
	v_rsq_f32_e32 v81, v81
	v_lshlrev_b32_e32 v91, 16, v67
	v_mul_f32_e32 v66, v66, v80
	v_mul_f32_e32 v66, v66, v91
	v_and_b32_e32 v67, 0xffff0000, v67
	v_cvt_pk_bf16_f32 v80, v84, v66
	v_mul_f32_e32 v66, v83, v81
	v_mul_f32_e32 v66, v66, v67
	v_cvt_pk_bf16_f32 v81, v82, v66
	v_lshlrev_b64 v[66:67], 12, v[200:201]
	v_lshl_add_u64 v[66:67], v[204:205], 0, v[66:67]
	global_store_dwordx4 v[66:67], v[78:81], off
	v_lshlrev_b32_e32 v95, 16, v160
	v_and_b32_e32 v96, 0xffff0000, v160
	v_lshlrev_b32_e32 v97, 16, v161
	v_and_b32_e32 v94, 0xffff0000, v161
	s_waitcnt vmcnt(6)
	v_mul_f32_e32 v90, 0xbfb8aa3b, v146
	v_mul_f32_e32 v91, 0xbfb8aa3b, v147
	v_mul_f32_e32 v92, 0xbfb8aa3b, v148
	v_mul_f32_e32 v93, 0xbfb8aa3b, v149
	v_mov_b32_e32 v82, v156
	v_mov_b32_e32 v83, v157
	v_mov_b32_e32 v84, v158
	v_mov_b32_e32 v85, v159
	v_mul_f32_e32 v78, 0xbfb8aa3b, v150
	v_mul_f32_e32 v79, 0xbfb8aa3b, v151
	v_mul_f32_e32 v80, 0xbfb8aa3b, v152
	v_mul_f32_e32 v81, 0xbfb8aa3b, v153
	v_fma_f32 v62, v62, v243, v90
	v_exp_f32_e32 v62, v62
	v_fma_f32 v58, v58, v243, v78
	v_exp_f32_e32 v58, v58
	v_add_f32_e32 v62, 1.0, v62
	v_rcp_f32_e64 v62, -v62
	v_add_f32_e32 v58, 1.0, v58
	v_fma_f32 v59, v59, v243, v79
	v_mul_f32_e32 v62, v82, v62
	v_mul_f32_e32 v102, 0x4038aa3b, v62
	v_exp_f32_e32 v102, v102
	v_exp_f32_e32 v59, v59
	v_fma_f32 v60, v60, v243, v80
	v_sub_f32_e32 v102, 1.0, v102
	v_max_f32_e32 v102, 0x1e3ce508, v102
	v_mul_f32_e32 v103, v58, v102
	v_mul_f32_e32 v58, v58, v103
	v_rsq_f32_e32 v58, v58
	v_add_f32_e32 v59, 1.0, v59
	v_exp_f32_e32 v60, v60
	v_mul_f32_e32 v58, v102, v58
	v_mul_f32_e32 v58, v58, v95
	v_cvt_pk_bf16_f32 v58, v62, v58
	v_fma_f32 v62, v63, v243, v91
	v_exp_f32_e32 v62, v62
	v_add_f32_e32 v60, 1.0, v60
	v_fma_f32 v61, v61, v243, v81
	v_exp_f32_e32 v61, v61
	v_add_f32_e32 v62, 1.0, v62
	v_rcp_f32_e64 v62, -v62
	v_add_f32_e32 v61, 1.0, v61
	v_mul_f32_e32 v62, v83, v62
	v_mul_f32_e32 v63, 0x4038aa3b, v62
	v_exp_f32_e32 v63, v63
	s_nop 0
	v_sub_f32_e32 v63, 1.0, v63
	v_max_f32_e32 v63, 0x1e3ce508, v63
	v_mul_f32_e32 v95, v59, v63
	v_mul_f32_e32 v59, v59, v95
	v_rsq_f32_e32 v59, v59
	s_nop 0
	v_mul_f32_e32 v59, v63, v59
	v_mul_f32_e32 v59, v59, v96
	v_cvt_pk_bf16_f32 v59, v62, v59
	v_fma_f32 v62, v64, v243, v92
	v_exp_f32_e32 v62, v62
	s_nop 0
	v_add_f32_e32 v62, 1.0, v62
	v_rcp_f32_e64 v62, -v62
	s_nop 0
	v_mul_f32_e32 v62, v84, v62
	v_mul_f32_e32 v63, 0x4038aa3b, v62
	v_exp_f32_e32 v63, v63
	s_nop 0
	v_sub_f32_e32 v63, 1.0, v63
	v_max_f32_e32 v63, 0x1e3ce508, v63
	v_mul_f32_e32 v64, v60, v63
	v_mul_f32_e32 v60, v60, v64
	v_rsq_f32_e32 v60, v60
	s_nop 0
	v_mul_f32_e32 v60, v63, v60
	v_mul_f32_e32 v60, v60, v97
	v_cvt_pk_bf16_f32 v60, v62, v60
	v_fma_f32 v62, v65, v243, v93
	v_exp_f32_e32 v62, v62
	s_nop 0
	v_add_f32_e32 v62, 1.0, v62
	v_rcp_f32_e64 v62, -v62
	s_nop 0
	v_mul_f32_e32 v62, v85, v62
	v_mul_f32_e32 v63, 0x4038aa3b, v62
	v_exp_f32_e32 v63, v63
	s_nop 0
	v_sub_f32_e32 v63, 1.0, v63
	v_max_f32_e32 v63, 0x1e3ce508, v63
	v_mul_f32_e32 v64, v61, v63
	v_mul_f32_e32 v61, v61, v64
	v_rsq_f32_e32 v61, v61
	s_nop 0
	v_mul_f32_e32 v61, v63, v61
	v_mul_f32_e32 v61, v61, v94
	v_cvt_pk_bf16_f32 v61, v62, v61
	global_store_dwordx4 v[154:155], v[58:61], off offset:16
	v_fma_f32 v54, v54, v243, v90
	v_exp_f32_e32 v54, v54
	v_fma_f32 v50, v50, v243, v78
	v_exp_f32_e32 v50, v50
	v_add_f32_e32 v54, 1.0, v54
	v_rcp_f32_e64 v54, -v54
	v_fma_f32 v55, v55, v243, v91
	v_add_f32_e32 v50, 1.0, v50
	v_mul_f32_e32 v54, v82, v54
	v_mul_f32_e32 v61, 0x4038aa3b, v54
	v_exp_f32_e32 v61, v61
	v_exp_f32_e32 v55, v55
	v_lshlrev_b32_e32 v58, 16, v124
	v_sub_f32_e32 v61, 1.0, v61
	v_max_f32_e32 v61, 0x1e3ce508, v61
	v_mul_f32_e32 v62, v50, v61
	v_mul_f32_e32 v50, v50, v62
	v_rsq_f32_e32 v50, v50
	v_add_f32_e32 v55, 1.0, v55
	v_rcp_f32_e64 v55, -v55
	v_fma_f32 v51, v51, v243, v79
	v_mul_f32_e32 v50, v61, v50
	v_mul_f32_e32 v50, v50, v58
	v_cvt_pk_bf16_f32 v50, v54, v50
	v_mul_f32_e32 v54, v83, v55
	v_mul_f32_e32 v55, 0x4038aa3b, v54
	v_exp_f32_e32 v55, v55
	v_exp_f32_e32 v51, v51
	v_fma_f32 v56, v56, v243, v92
	v_sub_f32_e32 v55, 1.0, v55
	v_exp_f32_e32 v56, v56
	v_max_f32_e32 v55, 0x1e3ce508, v55
	v_add_f32_e32 v51, 1.0, v51
	v_mul_f32_e32 v58, v51, v55
	v_mul_f32_e32 v51, v51, v58
	v_rsq_f32_e32 v51, v51
	v_add_f32_e32 v56, 1.0, v56
	v_rcp_f32_e64 v56, -v56
	v_mul_f32_e32 v51, v55, v51
	v_fma_f32 v55, v57, v243, v93
	v_mul_f32_e32 v56, v84, v56
	v_exp_f32_e32 v55, v55
	v_mul_f32_e32 v58, 0x4038aa3b, v56
	v_exp_f32_e32 v58, v58
	v_fma_f32 v52, v52, v243, v80
	v_exp_f32_e32 v52, v52
	v_add_f32_e32 v55, 1.0, v55
	v_and_b32_e32 v59, 0xffff0000, v124
	v_rcp_f32_e64 v55, -v55
	v_mul_f32_e32 v51, v51, v59
	v_cvt_pk_bf16_f32 v51, v54, v51
	v_sub_f32_e32 v54, 1.0, v58
	v_max_f32_e32 v54, 0x1e3ce508, v54
	v_add_f32_e32 v52, 1.0, v52
	v_mul_f32_e32 v57, v52, v54
	v_mul_f32_e32 v55, v85, v55
	v_mul_f32_e32 v52, v52, v57
	v_mul_f32_e32 v57, 0x4038aa3b, v55
	v_exp_f32_e32 v57, v57
	v_fma_f32 v53, v53, v243, v81
	v_exp_f32_e32 v53, v53
	v_rsq_f32_e32 v52, v52
	v_sub_f32_e32 v57, 1.0, v57
	v_max_f32_e32 v57, 0x1e3ce508, v57
	v_add_f32_e32 v53, 1.0, v53
	v_mul_f32_e32 v58, v53, v57
	v_mul_f32_e32 v53, v53, v58
	v_rsq_f32_e32 v53, v53
	v_lshlrev_b32_e32 v60, 16, v125
	v_and_b32_e32 v62, 0xffff0000, v125
	v_mul_f32_e32 v52, v54, v52
	v_mul_f32_e32 v53, v57, v53
	v_mul_f32_e32 v52, v52, v60
	v_mul_f32_e32 v53, v53, v62
	v_cvt_pk_bf16_f32 v52, v56, v52
	v_cvt_pk_bf16_f32 v53, v55, v53
	global_store_dwordx4 v[122:123], v[50:53], off offset:16
	v_fma_f32 v46, v46, v243, v90
	v_exp_f32_e32 v46, v46
	v_fma_f32 v42, v42, v243, v78
	v_exp_f32_e32 v42, v42
	v_add_f32_e32 v46, 1.0, v46
	v_rcp_f32_e64 v46, -v46
	v_fma_f32 v47, v47, v243, v91
	v_add_f32_e32 v42, 1.0, v42
	v_mul_f32_e32 v46, v82, v46
	v_mul_f32_e32 v53, 0x4038aa3b, v46
	v_exp_f32_e32 v53, v53
	v_exp_f32_e32 v47, v47
	v_lshlrev_b32_e32 v50, 16, v112
	v_sub_f32_e32 v53, 1.0, v53
	v_max_f32_e32 v53, 0x1e3ce508, v53
	v_mul_f32_e32 v54, v42, v53
	v_mul_f32_e32 v42, v42, v54
	v_rsq_f32_e32 v42, v42
	v_add_f32_e32 v47, 1.0, v47
	v_rcp_f32_e64 v47, -v47
	v_fma_f32 v43, v43, v243, v79
	v_mul_f32_e32 v42, v53, v42
	v_mul_f32_e32 v42, v42, v50
	v_cvt_pk_bf16_f32 v42, v46, v42
	v_mul_f32_e32 v46, v83, v47
	v_mul_f32_e32 v47, 0x4038aa3b, v46
	v_exp_f32_e32 v47, v47
	v_exp_f32_e32 v43, v43
	v_fma_f32 v48, v48, v243, v92
	v_sub_f32_e32 v47, 1.0, v47
	v_exp_f32_e32 v48, v48
	v_max_f32_e32 v47, 0x1e3ce508, v47
	v_add_f32_e32 v43, 1.0, v43
	v_mul_f32_e32 v50, v43, v47
	v_mul_f32_e32 v43, v43, v50
	v_rsq_f32_e32 v43, v43
	v_add_f32_e32 v48, 1.0, v48
	v_rcp_f32_e64 v48, -v48
	v_mul_f32_e32 v43, v47, v43
	v_fma_f32 v47, v49, v243, v93
	v_mul_f32_e32 v48, v84, v48
	v_exp_f32_e32 v47, v47
	v_mul_f32_e32 v50, 0x4038aa3b, v48
	v_exp_f32_e32 v50, v50
	v_fma_f32 v44, v44, v243, v80
	v_exp_f32_e32 v44, v44
	v_add_f32_e32 v47, 1.0, v47
	v_and_b32_e32 v51, 0xffff0000, v112
	v_rcp_f32_e64 v47, -v47
	v_mul_f32_e32 v43, v43, v51
	v_cvt_pk_bf16_f32 v43, v46, v43
	v_sub_f32_e32 v46, 1.0, v50
	v_max_f32_e32 v46, 0x1e3ce508, v46
	v_add_f32_e32 v44, 1.0, v44
	v_mul_f32_e32 v49, v44, v46
	v_mul_f32_e32 v47, v85, v47
	v_mul_f32_e32 v44, v44, v49
	v_mul_f32_e32 v49, 0x4038aa3b, v47
	v_exp_f32_e32 v49, v49
	v_fma_f32 v45, v45, v243, v81
	v_exp_f32_e32 v45, v45
	v_rsq_f32_e32 v44, v44
	v_sub_f32_e32 v49, 1.0, v49
	v_max_f32_e32 v49, 0x1e3ce508, v49
	v_add_f32_e32 v45, 1.0, v45
	v_mul_f32_e32 v50, v45, v49
	v_mul_f32_e32 v45, v45, v50
	v_rsq_f32_e32 v45, v45
	v_lshlrev_b32_e32 v52, 16, v113
	v_and_b32_e32 v54, 0xffff0000, v113
	v_mul_f32_e32 v44, v46, v44
	v_mul_f32_e32 v45, v49, v45
	v_mul_f32_e32 v44, v44, v52
	v_mul_f32_e32 v45, v45, v54
	v_cvt_pk_bf16_f32 v44, v48, v44
	v_cvt_pk_bf16_f32 v45, v47, v45
	global_store_dwordx4 v[110:111], v[42:45], off offset:16
	v_fma_f32 v38, v38, v243, v90
	v_exp_f32_e32 v38, v38
	v_fma_f32 v34, v34, v243, v78
	v_exp_f32_e32 v34, v34
	v_add_f32_e32 v38, 1.0, v38
	v_rcp_f32_e64 v38, -v38
	v_fma_f32 v39, v39, v243, v91
	v_add_f32_e32 v34, 1.0, v34
	v_mul_f32_e32 v38, v82, v38
	v_mul_f32_e32 v45, 0x4038aa3b, v38
	v_exp_f32_e32 v45, v45
	v_exp_f32_e32 v39, v39
	v_lshlrev_b32_e32 v42, 16, v100
	v_sub_f32_e32 v45, 1.0, v45
	v_max_f32_e32 v45, 0x1e3ce508, v45
	v_mul_f32_e32 v46, v34, v45
	v_mul_f32_e32 v34, v34, v46
	v_rsq_f32_e32 v34, v34
	v_add_f32_e32 v39, 1.0, v39
	v_rcp_f32_e64 v39, -v39
	v_fma_f32 v35, v35, v243, v79
	v_mul_f32_e32 v34, v45, v34
	v_mul_f32_e32 v34, v34, v42
	v_cvt_pk_bf16_f32 v34, v38, v34
	v_mul_f32_e32 v38, v83, v39
	v_mul_f32_e32 v39, 0x4038aa3b, v38
	v_exp_f32_e32 v39, v39
	v_exp_f32_e32 v35, v35
	v_fma_f32 v40, v40, v243, v92
	v_sub_f32_e32 v39, 1.0, v39
	v_exp_f32_e32 v40, v40
	v_max_f32_e32 v39, 0x1e3ce508, v39
	v_add_f32_e32 v35, 1.0, v35
	v_mul_f32_e32 v42, v35, v39
	v_mul_f32_e32 v35, v35, v42
	v_rsq_f32_e32 v35, v35
	v_add_f32_e32 v40, 1.0, v40
	v_rcp_f32_e64 v40, -v40
	v_mul_f32_e32 v35, v39, v35
	v_fma_f32 v39, v41, v243, v93
	v_mul_f32_e32 v40, v84, v40
	v_exp_f32_e32 v39, v39
	v_mul_f32_e32 v42, 0x4038aa3b, v40
	v_exp_f32_e32 v42, v42
	v_fma_f32 v36, v36, v243, v80
	v_exp_f32_e32 v36, v36
	v_add_f32_e32 v39, 1.0, v39
	v_and_b32_e32 v43, 0xffff0000, v100
	v_rcp_f32_e64 v39, -v39
	v_mul_f32_e32 v35, v35, v43
	v_cvt_pk_bf16_f32 v35, v38, v35
	v_sub_f32_e32 v38, 1.0, v42
	v_max_f32_e32 v38, 0x1e3ce508, v38
	v_add_f32_e32 v36, 1.0, v36
	v_mul_f32_e32 v41, v36, v38
	v_mul_f32_e32 v39, v85, v39
	v_mul_f32_e32 v36, v36, v41
	v_mul_f32_e32 v41, 0x4038aa3b, v39
	v_exp_f32_e32 v41, v41
	v_fma_f32 v37, v37, v243, v81
	v_exp_f32_e32 v37, v37
	v_rsq_f32_e32 v36, v36
	v_sub_f32_e32 v41, 1.0, v41
	v_max_f32_e32 v41, 0x1e3ce508, v41
	v_add_f32_e32 v37, 1.0, v37
	v_mul_f32_e32 v42, v37, v41
	v_mul_f32_e32 v37, v37, v42
	v_rsq_f32_e32 v37, v37
	v_lshlrev_b32_e32 v44, 16, v101
	v_and_b32_e32 v46, 0xffff0000, v101
	v_mul_f32_e32 v36, v38, v36
	v_mul_f32_e32 v37, v41, v37
	v_mul_f32_e32 v36, v36, v44
	v_mul_f32_e32 v37, v37, v46
	v_cvt_pk_bf16_f32 v36, v40, v36
	v_cvt_pk_bf16_f32 v37, v39, v37
	global_store_dwordx4 v[98:99], v[34:37], off offset:16
	v_fma_f32 v30, v30, v243, v90
	v_exp_f32_e32 v30, v30
	v_fma_f32 v26, v26, v243, v78
	v_exp_f32_e32 v26, v26
	v_add_f32_e32 v30, 1.0, v30
	v_rcp_f32_e64 v30, -v30
	v_fma_f32 v31, v31, v243, v91
	v_add_f32_e32 v26, 1.0, v26
	v_mul_f32_e32 v30, v82, v30
	v_mul_f32_e32 v37, 0x4038aa3b, v30
	v_exp_f32_e32 v37, v37
	v_exp_f32_e32 v31, v31
	v_lshlrev_b32_e32 v34, 16, v88
	v_sub_f32_e32 v37, 1.0, v37
	v_max_f32_e32 v37, 0x1e3ce508, v37
	v_mul_f32_e32 v38, v26, v37
	v_mul_f32_e32 v26, v26, v38
	v_rsq_f32_e32 v26, v26
	v_add_f32_e32 v31, 1.0, v31
	v_rcp_f32_e64 v31, -v31
	v_fma_f32 v27, v27, v243, v79
	v_mul_f32_e32 v26, v37, v26
	v_mul_f32_e32 v26, v26, v34
	v_cvt_pk_bf16_f32 v26, v30, v26
	v_mul_f32_e32 v30, v83, v31
	v_mul_f32_e32 v31, 0x4038aa3b, v30
	v_exp_f32_e32 v31, v31
	v_exp_f32_e32 v27, v27
	v_fma_f32 v32, v32, v243, v92
	v_sub_f32_e32 v31, 1.0, v31
	v_exp_f32_e32 v32, v32
	v_max_f32_e32 v31, 0x1e3ce508, v31
	v_add_f32_e32 v27, 1.0, v27
	v_mul_f32_e32 v34, v27, v31
	v_mul_f32_e32 v27, v27, v34
	v_rsq_f32_e32 v27, v27
	v_add_f32_e32 v32, 1.0, v32
	v_rcp_f32_e64 v32, -v32
	v_mul_f32_e32 v27, v31, v27
	v_fma_f32 v31, v33, v243, v93
	v_mul_f32_e32 v32, v84, v32
	v_exp_f32_e32 v31, v31
	v_mul_f32_e32 v34, 0x4038aa3b, v32
	v_exp_f32_e32 v34, v34
	v_fma_f32 v28, v28, v243, v80
	v_exp_f32_e32 v28, v28
	v_add_f32_e32 v31, 1.0, v31
	v_and_b32_e32 v35, 0xffff0000, v88
	v_rcp_f32_e64 v31, -v31
	v_mul_f32_e32 v27, v27, v35
	v_cvt_pk_bf16_f32 v27, v30, v27
	v_sub_f32_e32 v30, 1.0, v34
	v_max_f32_e32 v30, 0x1e3ce508, v30
	v_add_f32_e32 v28, 1.0, v28
	v_mul_f32_e32 v33, v28, v30
	v_mul_f32_e32 v31, v85, v31
	v_mul_f32_e32 v28, v28, v33
	v_mul_f32_e32 v33, 0x4038aa3b, v31
	v_exp_f32_e32 v33, v33
	v_fma_f32 v29, v29, v243, v81
	v_exp_f32_e32 v29, v29
	v_rsq_f32_e32 v28, v28
	v_sub_f32_e32 v33, 1.0, v33
	v_max_f32_e32 v33, 0x1e3ce508, v33
	v_add_f32_e32 v29, 1.0, v29
	v_mul_f32_e32 v34, v29, v33
	v_mul_f32_e32 v29, v29, v34
	v_rsq_f32_e32 v29, v29
	v_lshlrev_b32_e32 v36, 16, v89
	v_and_b32_e32 v38, 0xffff0000, v89
	v_mul_f32_e32 v28, v30, v28
	v_mul_f32_e32 v29, v33, v29
	v_mul_f32_e32 v28, v28, v36
	v_mul_f32_e32 v29, v29, v38
	v_cvt_pk_bf16_f32 v28, v32, v28
	v_cvt_pk_bf16_f32 v29, v31, v29
	global_store_dwordx4 v[86:87], v[26:29], off offset:16
	v_fma_f32 v22, v22, v243, v90
	v_exp_f32_e32 v22, v22
	v_fma_f32 v18, v18, v243, v78
	v_exp_f32_e32 v18, v18
	v_add_f32_e32 v22, 1.0, v22
	v_rcp_f32_e64 v22, -v22
	v_fma_f32 v23, v23, v243, v91
	v_add_f32_e32 v18, 1.0, v18
	v_mul_f32_e32 v22, v82, v22
	v_mul_f32_e32 v29, 0x4038aa3b, v22
	v_exp_f32_e32 v29, v29
	v_exp_f32_e32 v23, v23
	v_lshlrev_b32_e32 v26, 16, v76
	v_sub_f32_e32 v29, 1.0, v29
	v_max_f32_e32 v29, 0x1e3ce508, v29
	v_mul_f32_e32 v30, v18, v29
	v_mul_f32_e32 v18, v18, v30
	v_rsq_f32_e32 v18, v18
	v_add_f32_e32 v23, 1.0, v23
	v_rcp_f32_e64 v23, -v23
	v_fma_f32 v19, v19, v243, v79
	v_mul_f32_e32 v18, v29, v18
	v_mul_f32_e32 v18, v18, v26
	v_cvt_pk_bf16_f32 v18, v22, v18
	v_mul_f32_e32 v22, v83, v23
	v_mul_f32_e32 v23, 0x4038aa3b, v22
	v_exp_f32_e32 v23, v23
	v_exp_f32_e32 v19, v19
	v_fma_f32 v24, v24, v243, v92
	v_sub_f32_e32 v23, 1.0, v23
	v_exp_f32_e32 v24, v24
	v_max_f32_e32 v23, 0x1e3ce508, v23
	v_add_f32_e32 v19, 1.0, v19
	v_mul_f32_e32 v26, v19, v23
	v_mul_f32_e32 v19, v19, v26
	v_rsq_f32_e32 v19, v19
	v_add_f32_e32 v24, 1.0, v24
	v_rcp_f32_e64 v24, -v24
	v_mul_f32_e32 v19, v23, v19
	v_fma_f32 v23, v25, v243, v93
	v_mul_f32_e32 v24, v84, v24
	v_exp_f32_e32 v23, v23
	v_mul_f32_e32 v26, 0x4038aa3b, v24
	v_exp_f32_e32 v26, v26
	v_fma_f32 v20, v20, v243, v80
	v_exp_f32_e32 v20, v20
	v_add_f32_e32 v23, 1.0, v23
	v_and_b32_e32 v27, 0xffff0000, v76
	v_rcp_f32_e64 v23, -v23
	v_mul_f32_e32 v19, v19, v27
	v_cvt_pk_bf16_f32 v19, v22, v19
	v_sub_f32_e32 v22, 1.0, v26
	v_max_f32_e32 v22, 0x1e3ce508, v22
	v_add_f32_e32 v20, 1.0, v20
	v_mul_f32_e32 v25, v20, v22
	v_mul_f32_e32 v23, v85, v23
	v_mul_f32_e32 v20, v20, v25
	v_mul_f32_e32 v25, 0x4038aa3b, v23
	v_exp_f32_e32 v25, v25
	v_fma_f32 v21, v21, v243, v81
	v_exp_f32_e32 v21, v21
	v_rsq_f32_e32 v20, v20
	v_sub_f32_e32 v25, 1.0, v25
	v_max_f32_e32 v25, 0x1e3ce508, v25
	v_add_f32_e32 v21, 1.0, v21
	v_mul_f32_e32 v26, v21, v25
	v_mul_f32_e32 v21, v21, v26
	v_rsq_f32_e32 v21, v21
	v_lshlrev_b32_e32 v28, 16, v77
	v_and_b32_e32 v30, 0xffff0000, v77
	v_mul_f32_e32 v20, v22, v20
	v_mul_f32_e32 v21, v25, v21
	v_mul_f32_e32 v20, v20, v28
	v_mul_f32_e32 v21, v21, v30
	v_cvt_pk_bf16_f32 v20, v24, v20
	v_cvt_pk_bf16_f32 v21, v23, v21
	global_store_dwordx4 v[74:75], v[18:21], off offset:16
	v_fma_f32 v14, v14, v243, v90
	v_exp_f32_e32 v14, v14
	v_fma_f32 v10, v10, v243, v78
	v_exp_f32_e32 v10, v10
	v_add_f32_e32 v14, 1.0, v14
	v_rcp_f32_e64 v14, -v14
	v_fma_f32 v15, v15, v243, v91
	v_add_f32_e32 v10, 1.0, v10
	v_mul_f32_e32 v14, v82, v14
	v_mul_f32_e32 v21, 0x4038aa3b, v14
	v_exp_f32_e32 v21, v21
	v_exp_f32_e32 v15, v15
	v_lshlrev_b32_e32 v18, 16, v72
	v_sub_f32_e32 v21, 1.0, v21
	v_max_f32_e32 v21, 0x1e3ce508, v21
	v_mul_f32_e32 v22, v10, v21
	v_mul_f32_e32 v10, v10, v22
	v_rsq_f32_e32 v10, v10
	v_add_f32_e32 v15, 1.0, v15
	v_rcp_f32_e64 v15, -v15
	v_fma_f32 v11, v11, v243, v79
	v_mul_f32_e32 v10, v21, v10
	v_mul_f32_e32 v10, v10, v18
	v_cvt_pk_bf16_f32 v10, v14, v10
	v_mul_f32_e32 v14, v83, v15
	v_mul_f32_e32 v15, 0x4038aa3b, v14
	v_exp_f32_e32 v15, v15
	v_exp_f32_e32 v11, v11
	v_fma_f32 v16, v16, v243, v92
	v_sub_f32_e32 v15, 1.0, v15
	v_exp_f32_e32 v16, v16
	v_max_f32_e32 v15, 0x1e3ce508, v15
	v_add_f32_e32 v11, 1.0, v11
	v_mul_f32_e32 v18, v11, v15
	v_mul_f32_e32 v11, v11, v18
	v_rsq_f32_e32 v11, v11
	v_add_f32_e32 v16, 1.0, v16
	v_rcp_f32_e64 v16, -v16
	v_mul_f32_e32 v11, v15, v11
	v_fma_f32 v15, v17, v243, v93
	v_mul_f32_e32 v16, v84, v16
	v_exp_f32_e32 v15, v15
	v_mul_f32_e32 v18, 0x4038aa3b, v16
	v_exp_f32_e32 v18, v18
	v_fma_f32 v12, v12, v243, v80
	v_exp_f32_e32 v12, v12
	v_add_f32_e32 v15, 1.0, v15
	v_and_b32_e32 v19, 0xffff0000, v72
	v_rcp_f32_e64 v15, -v15
	v_mul_f32_e32 v11, v11, v19
	v_cvt_pk_bf16_f32 v11, v14, v11
	v_sub_f32_e32 v14, 1.0, v18
	v_max_f32_e32 v14, 0x1e3ce508, v14
	v_add_f32_e32 v12, 1.0, v12
	v_mul_f32_e32 v17, v12, v14
	v_mul_f32_e32 v15, v85, v15
	v_mul_f32_e32 v12, v12, v17
	v_mul_f32_e32 v17, 0x4038aa3b, v15
	v_exp_f32_e32 v17, v17
	v_fma_f32 v13, v13, v243, v81
	v_exp_f32_e32 v13, v13
	v_rsq_f32_e32 v12, v12
	v_sub_f32_e32 v17, 1.0, v17
	v_max_f32_e32 v17, 0x1e3ce508, v17
	v_add_f32_e32 v13, 1.0, v13
	v_mul_f32_e32 v18, v13, v17
	v_mul_f32_e32 v13, v13, v18
	v_rsq_f32_e32 v13, v13
	v_lshlrev_b32_e32 v20, 16, v73
	v_and_b32_e32 v22, 0xffff0000, v73
	v_mul_f32_e32 v12, v14, v12
	v_mul_f32_e32 v13, v17, v13
	v_mul_f32_e32 v12, v12, v20
	v_mul_f32_e32 v13, v13, v22
	v_cvt_pk_bf16_f32 v12, v16, v12
	v_cvt_pk_bf16_f32 v13, v15, v13
	global_store_dwordx4 v[70:71], v[10:13], off offset:16
	v_fma_f32 v6, v6, v243, v90
	v_exp_f32_e32 v6, v6
	v_fma_f32 v2, v2, v243, v78
	v_exp_f32_e32 v2, v2
	v_add_f32_e32 v6, 1.0, v6
	v_rcp_f32_e64 v6, -v6
	v_fma_f32 v7, v7, v243, v91
	v_add_f32_e32 v2, 1.0, v2
	v_mul_f32_e32 v6, v82, v6
	v_mul_f32_e32 v13, 0x4038aa3b, v6
	v_exp_f32_e32 v13, v13
	v_exp_f32_e32 v7, v7
	v_lshlrev_b32_e32 v10, 16, v68
	v_sub_f32_e32 v13, 1.0, v13
	v_max_f32_e32 v13, 0x1e3ce508, v13
	v_mul_f32_e32 v14, v2, v13
	v_mul_f32_e32 v2, v2, v14
	v_rsq_f32_e32 v2, v2
	v_add_f32_e32 v7, 1.0, v7
	v_rcp_f32_e64 v7, -v7
	v_fma_f32 v3, v3, v243, v79
	v_mul_f32_e32 v2, v13, v2
	v_mul_f32_e32 v2, v2, v10
	v_cvt_pk_bf16_f32 v2, v6, v2
	v_mul_f32_e32 v6, v83, v7
	v_mul_f32_e32 v7, 0x4038aa3b, v6
	v_exp_f32_e32 v7, v7
	v_exp_f32_e32 v3, v3
	v_fma_f32 v8, v8, v243, v92
	v_sub_f32_e32 v7, 1.0, v7
	v_exp_f32_e32 v8, v8
	v_max_f32_e32 v7, 0x1e3ce508, v7
	v_add_f32_e32 v3, 1.0, v3
	v_mul_f32_e32 v10, v3, v7
	v_mul_f32_e32 v3, v3, v10
	v_rsq_f32_e32 v3, v3
	v_add_f32_e32 v8, 1.0, v8
	v_rcp_f32_e64 v8, -v8
	v_mul_f32_e32 v3, v7, v3
	v_fma_f32 v7, v9, v243, v93
	v_mul_f32_e32 v8, v84, v8
	v_exp_f32_e32 v7, v7
	v_mul_f32_e32 v10, 0x4038aa3b, v8
	v_exp_f32_e32 v10, v10
	v_fma_f32 v4, v4, v243, v80
	v_exp_f32_e32 v4, v4
	v_add_f32_e32 v7, 1.0, v7
	v_and_b32_e32 v11, 0xffff0000, v68
	v_rcp_f32_e64 v7, -v7
	v_mul_f32_e32 v3, v3, v11
	v_cvt_pk_bf16_f32 v3, v6, v3
	v_sub_f32_e32 v6, 1.0, v10
	v_max_f32_e32 v6, 0x1e3ce508, v6
	v_add_f32_e32 v4, 1.0, v4
	v_mul_f32_e32 v9, v4, v6
	v_mul_f32_e32 v7, v85, v7
	v_mul_f32_e32 v4, v4, v9
	v_mul_f32_e32 v9, 0x4038aa3b, v7
	v_exp_f32_e32 v9, v9
	v_fma_f32 v5, v5, v243, v81
	v_exp_f32_e32 v5, v5
	v_rsq_f32_e32 v4, v4
	v_sub_f32_e32 v9, 1.0, v9
	v_max_f32_e32 v9, 0x1e3ce508, v9
	v_add_f32_e32 v5, 1.0, v5
	v_mul_f32_e32 v10, v5, v9
	v_mul_f32_e32 v5, v5, v10
	v_rsq_f32_e32 v5, v5
	v_lshlrev_b32_e32 v12, 16, v69
	v_and_b32_e32 v14, 0xffff0000, v69
	v_mul_f32_e32 v4, v6, v4
	v_mul_f32_e32 v5, v9, v5
	v_mul_f32_e32 v4, v4, v12
	v_mul_f32_e32 v5, v5, v14
	v_cvt_pk_bf16_f32 v4, v8, v4
	v_cvt_pk_bf16_f32 v5, v7, v5
	global_store_dwordx4 v[66:67], v[2:5], off offset:16
	s_andn2_b64 vcc, exec, s[40:41]
	s_mov_b64 s[0:1], -1
	s_cbranch_vccnz .LBB0_993
	s_andn2_b64 vcc, exec, s[44:45]
	s_cbranch_vccnz .LBB0_992
	s_barrier
	s_branch .LBB0_992
